# k6 refinements: aggregate-counter poll issued with the SBG count-in; K-loop poll issued one iteration early
# baseline (speedup 1.0000x reference)
.LBB0_299:
	s_waitcnt vmcnt(0)
	s_barrier
	s_mov_b64 s[0:1], exec
	v_readlane_b32 s4, v246, 2
	v_readlane_b32 s5, v246, 3
	s_and_b64 s[4:5], s[0:1], s[4:5]
	s_mov_b64 exec, s[4:5]
	s_cbranch_execz .LBB0_308
	v_mov_b32_e32 v2, 0
	s_lshl_b32 s98, s33, 8
	s_add_u32 s98, s98, 0x560c0
	s_add_u32 s98, s92, s98
	s_addc_u32 s99, s93, 0
	v_mov_b32_e32 v3, 1
	global_atomic_add v3, v2, v3, s[98:99] sc0
	s_add_u32 s4, s92, 0x3900
	s_addc_u32 s5, s93, 0
	global_load_dword v250, v2, s[4:5] sc1
	v_readlane_b32 s100, v246, 8
	s_waitcnt vmcnt(0)
	v_readfirstlane_b32 s101, v3
	s_add_u32 s101, s101, 1
	s_cmp_lg_u32 s101, s100
	s_cbranch_scc1 .Lsbg_done
	buffer_wbl2 sc1
	s_waitcnt vmcnt(0)
	s_add_u32 s98, s92, 0x57180
	s_addc_u32 s99, s93, 0
	v_mov_b32_e32 v3, s100
	global_atomic_add v2, v3, s[98:99]
.Lsbg_done:
	v_cmp_le_u32_e32 vcc, s3, v250
	s_cbranch_vccnz .LBB0_308
	s_add_u32 s4, s92, 0x3900
	s_addc_u32 s5, s93, 0
	s_mov_b32 s8, 0x400001
	s_waitcnt vmcnt(7)
	v_mov_b32_e32 v2, 0
	s_branch .LBB0_302

.LBB0_624:
	s_cmpk_lg_i32 s40, 0x400
	s_cbranch_scc1 .Lk6_noearly
	s_mov_b64 s[100:101], exec
	v_readlane_b32 s98, v246, 2
	v_readlane_b32 s99, v246, 3
	s_and_b64 s[98:99], s[100:101], s[98:99]
	s_mov_b64 exec, s[98:99]
	s_cbranch_execz .Lk6_early_end
	s_add_u32 s98, s92, 0x57100
	s_addc_u32 s99, s93, 0
	v_mov_b32_e32 v250, 0
	global_load_dword v251, v250, s[98:99] sc1

.Lk6_noearly:
	s_cmpk_lg_i32 s40, 0x500
	s_cbranch_scc1 .Lk6_go
	s_mov_b64 s[100:101], exec
	v_readlane_b32 s98, v246, 2
	v_readlane_b32 s99, v246, 3
	s_and_b64 s[98:99], s[100:101], s[98:99]
	s_mov_b64 exec, s[98:99]
	s_cbranch_execz .Lk6_chk_end
	s_add_u32 s98, s92, 0x57100
	s_addc_u32 s99, s93, 0
	v_mov_b32_e32 v250, 0
	v_mov_b32_e32 v252, 0x400000
	s_waitcnt vmcnt(0)
	v_cmp_gt_u32_e32 vcc, 0x100, v251
	s_cbranch_vccz .Lk6_chk_end
